# hnorm phase: nontemporal (nt) hint on the streaming f32 row loads / bf16 delta loads and on the f32 x stores (bf16 h stores stay cached for gemm_in)
# speedup vs baseline: 1.0114x; 1.0114x over previous
.LBB0_33:
	v_readlane_b32 s0, v253, 34
	v_readlane_b32 s1, v253, 35
	v_mov_b32_e32 v2, v143
	v_writelane_b32 v255, s0, 25
	s_mul_i32 s96, s4, 0x6c00
	v_ashrrev_i32_e32 v182, 6, v2
	v_writelane_b32 v255, s1, 26
	s_lshl_b64 s[0:1], s[96:97], 2
	v_readlane_b32 s6, v253, 36
	v_and_b32_e32 v97, 7, v182
	v_readlane_b32 s7, v253, 37
	s_add_u32 s0, s6, s0
	v_readlane_b32 s68, v253, 1
	v_mul_u32_u24_e32 v0, 0xc00, v97
	s_addc_u32 s1, s7, s1
	s_lshl_b32 s96, s4, 10
	v_readlane_b32 s76, v253, 9
	v_readlane_b32 s77, v253, 10
	v_lshlrev_b32_e32 v128, 2, v0
	v_lshlrev_b32_e32 v2, 2, v2
	s_mov_b32 s56, s4
	s_lshl_b64 s[4:5], s[96:97], 2
	s_mov_b64 s[16:17], s[76:77]
	v_lshl_add_u64 v[0:1], s[0:1], 0, v[128:129]
	v_lshl_add_u64 v[4:5], s[6:7], 0, v[128:129]
	v_and_b32_e32 v96, 0xfc, v2
	s_mov_b64 s[6:7], 0x1000
	s_add_u32 s4, s16, s4
	v_lshl_add_u64 v[24:25], v[0:1], 0, s[6:7]
	v_lshlrev_b32_e32 v128, 2, v96
	s_addc_u32 s5, s17, s5
	v_lshl_add_u64 v[2:3], v[24:25], 0, v[128:129]
	global_load_dwordx4 v[64:67], v128, s[4:5] nt
	v_lshl_add_u64 v[26:27], v[0:1], 0, v[128:129]
	global_load_dwordx4 v[68:71], v[2:3], off nt
	s_nop 0
	global_load_dwordx4 v[0:3], v[26:27], off nt
	s_mov_b64 s[6:7], 0x2000
	v_lshl_add_u64 v[32:33], v[4:5], 0, s[6:7]
	s_and_b64 vcc, exec, s[10:11]
	v_mov_b32_e32 v4, v129
	v_mov_b32_e32 v5, v129
	v_mov_b32_e32 v6, v129
	v_mov_b32_e32 v7, v129
	v_readlane_b32 s69, v253, 2
	v_readlane_b32 s70, v253, 3
	v_readlane_b32 s71, v253, 4
	v_readlane_b32 s72, v253, 5
	v_readlane_b32 s73, v253, 6
	v_readlane_b32 s74, v253, 7
	v_readlane_b32 s75, v253, 8
	v_readlane_b32 s78, v253, 11
	v_readlane_b32 s79, v253, 12
	v_readlane_b32 s80, v253, 13
	v_readlane_b32 s81, v253, 14
	v_readlane_b32 s82, v253, 15
	v_readlane_b32 s83, v253, 16
	s_cbranch_vccnz .LBB0_35
	v_lshl_add_u64 v[4:5], v[32:33], 0, v[128:129]
	global_load_dwordx4 v[4:7], v[4:5], off nt
.LBB0_35:
	v_or_b32_e32 v8, 0x100, v96
	v_lshlrev_b32_e32 v102, 2, v8
	v_mov_b32_e32 v103, v129
	v_lshl_add_u64 v[100:101], s[4:5], 0, v[128:129]
	v_lshl_add_u64 v[8:9], v[24:25], 0, v[102:103]
	global_load_dwordx4 v[72:75], v[100:101], off offset:1024 nt
	global_load_dwordx4 v[76:79], v[8:9], off nt
	s_nop 0
	global_load_dwordx4 v[8:11], v[26:27], off offset:1024 nt
	s_xor_b64 s[4:5], s[10:11], -1
	v_cndmask_b32_e64 v13, 0, 1, s[4:5]
	v_writelane_b32 v255, s4, 27
	v_mov_b32_e32 v12, 0
	v_cmp_ne_u32_e64 s[8:9], 1, v13
	v_writelane_b32 v255, s5, 28
	s_andn2_b64 vcc, exec, s[4:5]
	v_mov_b32_e32 v16, 0
	v_mov_b32_e32 v17, 0
	v_mov_b32_e32 v18, 0
	v_mov_b32_e32 v19, 0
	s_cbranch_vccnz .LBB0_37
	v_lshl_add_u64 v[14:15], v[32:33], 0, v[102:103]
	global_load_dwordx4 v[16:19], v[14:15], off nt
.LBB0_37:
	v_or_b32_e32 v13, 0x200, v96
	v_lshlrev_b32_e32 v104, 2, v13
	v_mov_b32_e32 v105, v129
	v_lshl_add_u64 v[14:15], v[24:25], 0, v[104:105]
	global_load_dwordx4 v[80:83], v[100:101], off offset:2048 nt
	global_load_dwordx4 v[84:87], v[14:15], off nt
	global_load_dwordx4 v[20:23], v[26:27], off offset:2048 nt
	s_and_b64 vcc, exec, s[8:9]
	v_mov_b32_e32 v13, 0
	v_mov_b32_e32 v14, 0
	v_mov_b32_e32 v15, 0
	s_cbranch_vccnz .LBB0_39
	v_lshl_add_u64 v[12:13], v[32:33], 0, v[104:105]
	global_load_dwordx4 v[12:15], v[12:13], off nt
.LBB0_39:
	v_or_b32_e32 v28, 0x300, v96
	v_lshlrev_b32_e32 v106, 2, v28
	v_mov_b32_e32 v107, v129
	v_lshl_add_u64 v[24:25], v[24:25], 0, v[106:107]
	global_load_dwordx4 v[88:91], v[100:101], off offset:3072 nt
	global_load_dwordx4 v[92:95], v[24:25], off nt
	s_nop 0
	global_load_dwordx4 v[24:27], v[26:27], off offset:3072 nt
	v_mov_b32_e32 v28, 0
	s_and_b64 vcc, exec, s[8:9]
	v_mov_b32_e32 v29, v28
	v_mov_b32_e32 v30, v28
	v_mov_b32_e32 v31, v28
	s_cbranch_vccnz .LBB0_41
	v_lshl_add_u64 v[28:29], v[32:33], 0, v[106:107]
	global_load_dwordx4 v[28:31], v[28:29], off nt
.LBB0_41:
	v_readlane_b32 s68, v253, 1
	v_add_u32_e32 v98, s52, v182
	v_lshlrev_b32_e32 v32, 24, v97
	v_mov_b32_e32 v33, v129
	v_readlane_b32 s69, v253, 2
	v_ashrrev_i32_e32 v172, 3, v98
	v_readlane_b32 s74, v253, 7
	v_lshl_add_u64 v[146:147], s[68:69], 0, v[32:33]
	v_lshlrev_b32_e32 v32, 23, v97
	v_lshl_add_u64 v[148:149], s[28:29], 0, v[32:33]
	v_cmp_gt_i32_e64 s[4:5], s85, v172
	v_readlane_b32 s70, v253, 3
	v_readlane_b32 s71, v253, 4
	v_readlane_b32 s72, v253, 5
	v_readlane_b32 s73, v253, 6
	v_readlane_b32 s75, v253, 8
	v_readlane_b32 s76, v253, 9
	v_readlane_b32 s77, v253, 10
	v_readlane_b32 s78, v253, 11
	v_readlane_b32 s79, v253, 12
	v_readlane_b32 s80, v253, 13
	v_readlane_b32 s81, v253, 14
	v_readlane_b32 s82, v253, 15
	v_readlane_b32 s83, v253, 16
	s_and_saveexec_b64 s[6:7], s[4:5]
	s_movk_i32 s18, 0x800
	s_mov_b32 s74, s56
	s_cbranch_execz .LBB0_44
	v_ashrrev_i32_e32 v173, 31, v172
	v_lshlrev_b64 v[32:33], 12, v[172:173]
	v_lshl_add_u64 v[32:33], v[146:147], 0, v[32:33]
	v_lshl_add_u64 v[44:45], v[32:33], 0, v[128:129]
	global_load_dwordx4 v[32:35], v[44:45], off nt
	global_load_dwordx4 v[36:39], v[44:45], off offset:1024 nt
	global_load_dwordx4 v[40:43], v[44:45], off offset:2048 nt
	s_nop 0
	global_load_dwordx4 v[44:47], v[44:45], off offset:3072 nt
	s_and_b64 vcc, exec, s[8:9]
	s_cbranch_vccnz .LBB0_44
	v_lshlrev_b64 v[48:49], 11, v[172:173]
	v_lshl_add_u64 v[48:49], v[148:149], 0, v[48:49]
	v_lshlrev_b32_e32 v50, 1, v96
	v_mov_b32_e32 v51, v129
	v_lshl_add_u64 v[48:49], v[48:49], 0, v[50:51]
	global_load_dwordx2 v[108:109], v[48:49], off nt
	global_load_dwordx2 v[110:111], v[48:49], off offset:512 nt
	global_load_dwordx2 v[112:113], v[48:49], off offset:1024 nt
	global_load_dwordx2 v[114:115], v[48:49], off offset:1536 nt
.LBB0_44:
	s_or_b64 exec, exec, s[6:7]
	v_readlane_b32 s6, v253, 40
	s_nop 1
	v_add_u32_e32 v168, s6, v172
	v_cmp_gt_i32_e32 vcc, s85, v168
	s_and_saveexec_b64 s[6:7], vcc
	s_cbranch_execz .LBB0_47
	v_ashrrev_i32_e32 v169, 31, v168
	v_lshlrev_b64 v[48:49], 12, v[168:169]
	v_lshl_add_u64 v[48:49], v[146:147], 0, v[48:49]
	v_lshl_add_u64 v[60:61], v[48:49], 0, v[128:129]
	global_load_dwordx4 v[48:51], v[60:61], off nt
	global_load_dwordx4 v[52:55], v[60:61], off offset:1024 nt
	global_load_dwordx4 v[56:59], v[60:61], off offset:2048 nt
	s_nop 0
	global_load_dwordx4 v[60:63], v[60:61], off offset:3072 nt
	s_and_b64 vcc, exec, s[8:9]
	s_cbranch_vccnz .LBB0_47
	v_lshlrev_b64 v[116:117], 11, v[168:169]
	v_lshl_add_u64 v[116:117], v[148:149], 0, v[116:117]
	v_lshlrev_b32_e32 v118, 1, v96
	v_mov_b32_e32 v119, v129
	v_lshl_add_u64 v[122:123], v[116:117], 0, v[118:119]
	global_load_dwordx2 v[116:117], v[122:123], off nt
	global_load_dwordx2 v[118:119], v[122:123], off offset:512 nt
	global_load_dwordx2 v[120:121], v[122:123], off offset:1024 nt
	s_nop 0
	global_load_dwordx2 v[122:123], v[122:123], off offset:1536 nt

.LBB0_52:
	v_add_u32_e32 v170, s53, v172
	v_cmp_gt_i32_e64 s[4:5], s85, v170
	v_ashrrev_i32_e32 v171, 31, v170
	s_and_saveexec_b64 s[14:15], s[4:5]
	s_cbranch_execz .LBB0_55
	v_lshlrev_b64 v[80:81], 12, v[170:171]
	v_lshl_add_u64 v[80:81], v[26:27], 0, v[80:81]
	global_load_dwordx4 v[92:95], v[80:81], off nt
	global_load_dwordx4 v[88:91], v[80:81], off offset:1024 nt
	global_load_dwordx4 v[84:87], v[80:81], off offset:2048 nt
	s_nop 0
	global_load_dwordx4 v[80:83], v[80:81], off offset:3072 nt
	s_and_b64 vcc, exec, s[8:9]
	s_cbranch_vccnz .LBB0_55
	v_lshlrev_b64 v[160:161], 11, v[170:171]
	v_lshl_add_u64 v[160:161], v[146:147], 0, v[160:161]
	global_load_dwordx2 v[166:167], v[160:161], off nt
	global_load_dwordx2 v[164:165], v[160:161], off offset:512 nt
	global_load_dwordx2 v[162:163], v[160:161], off offset:1024 nt
	s_nop 0
	global_load_dwordx2 v[160:161], v[160:161], off offset:1536 nt
.LBB0_55:
	s_or_b64 exec, exec, s[14:15]
	v_readlane_b32 s14, v253, 40
	s_mul_i32 s14, s14, 3
	s_nop 0
	v_add_u32_e32 v174, s14, v172
	v_cmp_gt_i32_e32 vcc, s85, v174
	s_and_saveexec_b64 s[14:15], vcc
	s_cbranch_execz .LBB0_58
	v_ashrrev_i32_e32 v175, 31, v174
	v_lshlrev_b64 v[64:65], 12, v[174:175]
	v_lshl_add_u64 v[64:65], v[26:27], 0, v[64:65]
	global_load_dwordx4 v[76:79], v[64:65], off nt
	global_load_dwordx4 v[72:75], v[64:65], off offset:1024 nt
	global_load_dwordx4 v[68:71], v[64:65], off offset:2048 nt
	s_nop 0
	global_load_dwordx4 v[64:67], v[64:65], off offset:3072 nt
	s_and_b64 vcc, exec, s[8:9]
	s_cbranch_vccnz .LBB0_58
	v_lshlrev_b64 v[152:153], 11, v[174:175]
	v_lshl_add_u64 v[152:153], v[146:147], 0, v[152:153]
	global_load_dwordx2 v[158:159], v[152:153], off nt
	global_load_dwordx2 v[156:157], v[152:153], off offset:512 nt
	global_load_dwordx2 v[154:155], v[152:153], off offset:1024 nt
	s_nop 0
	global_load_dwordx2 v[152:153], v[152:153], off offset:1536 nt
.LBB0_58:
	s_or_b64 exec, exec, s[14:15]
	s_and_b64 vcc, exec, s[8:9]
	v_ashrrev_i32_e32 v173, 31, v172
	s_cbranch_vccnz .LBB0_60
	v_lshlrev_b32_e32 v176, 16, v108
	v_and_b32_e32 v177, 0xffff0000, v108
	v_pk_fma_f32 v[32:33], v[4:5], v[176:177], v[32:33]
	v_lshlrev_b32_e32 v176, 16, v109
	v_and_b32_e32 v177, 0xffff0000, v109
	v_pk_fma_f32 v[34:35], v[6:7], v[176:177], v[34:35]
	v_lshlrev_b32_e32 v176, 16, v110
	v_and_b32_e32 v177, 0xffff0000, v110
	v_pk_fma_f32 v[36:37], v[16:17], v[176:177], v[36:37]
	v_lshlrev_b32_e32 v176, 16, v111
	v_and_b32_e32 v177, 0xffff0000, v111
	v_pk_fma_f32 v[38:39], v[18:19], v[176:177], v[38:39]
	v_lshlrev_b32_e32 v176, 16, v112
	v_and_b32_e32 v177, 0xffff0000, v112
	v_pk_fma_f32 v[40:41], v[12:13], v[176:177], v[40:41]
	v_lshlrev_b32_e32 v176, 16, v113
	v_and_b32_e32 v177, 0xffff0000, v113
	v_pk_fma_f32 v[42:43], v[14:15], v[176:177], v[42:43]
	v_lshlrev_b32_e32 v176, 16, v114
	v_and_b32_e32 v177, 0xffff0000, v114
	v_lshlrev_b64 v[174:175], 12, v[172:173]
	v_pk_fma_f32 v[44:45], v[28:29], v[176:177], v[44:45]
	v_lshlrev_b32_e32 v176, 16, v115
	v_and_b32_e32 v177, 0xffff0000, v115
	v_lshl_add_u64 v[174:175], v[148:149], 0, v[174:175]
	v_pk_fma_f32 v[46:47], v[30:31], v[176:177], v[46:47]
	global_store_dwordx4 v[174:175], v[32:35], off nt
	global_store_dwordx4 v[174:175], v[36:39], off offset:1024 nt
	global_store_dwordx4 v[174:175], v[40:43], off offset:2048 nt
	global_store_dwordx4 v[174:175], v[44:47], off offset:3072 nt
.LBB0_60:
	v_mul_f32_e32 v97, v33, v33
	v_mul_f32_e32 v99, v37, v37
	v_fmac_f32_e32 v97, v32, v32
	v_fmac_f32_e32 v99, v36, v36
	v_fmac_f32_e32 v97, v34, v34
	v_fmac_f32_e32 v99, v38, v38
	v_fmac_f32_e32 v97, v35, v35
	v_fmac_f32_e32 v99, v39, v39
	v_add_f32_e32 v97, v99, v97
	v_mul_f32_e32 v99, v41, v41
	v_fmac_f32_e32 v99, v40, v40
	v_fmac_f32_e32 v99, v42, v42
	v_fmac_f32_e32 v99, v43, v43
	v_add_f32_e32 v97, v99, v97
	v_mul_f32_e32 v99, v45, v45
	v_fmac_f32_e32 v99, v44, v44
	v_fmac_f32_e32 v99, v46, v46
	v_fmac_f32_e32 v99, v47, v47
	v_add_f32_e32 v97, v99, v97
	ds_swizzle_b32 v99, v97 offset:swizzle(SWAP,1)
	v_mov_b32_e32 v184, v33
	v_mov_b32_e32 v185, v35
	v_mov_b32_e32 v176, v32
	v_mov_b32_e32 v177, v34
	s_waitcnt lgkmcnt(0)
	v_add_f32_e32 v97, v97, v99
	ds_swizzle_b32 v99, v97 offset:swizzle(SWAP,2)
	v_lshlrev_b64 v[174:175], 11, v[172:173]
	v_lshl_add_u64 v[174:175], v[150:151], 0, v[174:175]
	s_waitcnt lgkmcnt(0)
	v_add_f32_e32 v97, v97, v99
	ds_swizzle_b32 v99, v97 offset:swizzle(SWAP,4)
	s_waitcnt lgkmcnt(0)
	v_add_f32_e32 v97, v97, v99
	ds_swizzle_b32 v99, v97 offset:swizzle(SWAP,8)
	s_waitcnt lgkmcnt(0)
	v_add_f32_e32 v97, v97, v99
	ds_swizzle_b32 v99, v97 offset:swizzle(SWAP,16)
	s_waitcnt lgkmcnt(0)
	v_add_f32_e32 v97, v97, v99
	v_mov_b32_e32 v99, v97
	s_nop 1
	v_permlane32_swap_b32_e32 v97, v99
	v_add_f32_e32 v97, v97, v99
	v_fmamk_f32 v97, v97, 0x3a800000, v142
	v_mul_f32_e32 v99, 0x4b800000, v97
	v_cmp_gt_f32_e32 vcc, s35, v97
	s_nop 1
	v_cndmask_b32_e32 v97, v97, v99, vcc
	v_rsq_f32_e32 v97, v97
	s_nop 0
	v_mul_f32_e32 v99, 0x45800000, v97
	v_cndmask_b32_e32 v186, v97, v99, vcc
	v_pk_mul_f32 v[184:185], v[184:185], v[186:187] op_sel_hi:[1,0]
	v_pk_mul_f32 v[176:177], v[176:177], v[186:187] op_sel_hi:[1,0]
	v_pk_fma_f32 v[184:185], v[140:141], v[184:185], v[144:145]
	v_pk_fma_f32 v[176:177], v[138:139], v[176:177], v[0:1]
	v_and_b32_sdwa v103, v185, v178 dst_sel:DWORD dst_unused:UNUSED_PAD src0_sel:WORD_1 src1_sel:DWORD
	v_and_b32_sdwa v105, v184, v178 dst_sel:DWORD dst_unused:UNUSED_PAD src0_sel:WORD_1 src1_sel:DWORD
	v_and_b32_sdwa v97, v177, v178 dst_sel:DWORD dst_unused:UNUSED_PAD src0_sel:WORD_1 src1_sel:DWORD
	v_and_b32_sdwa v99, v176, v178 dst_sel:DWORD dst_unused:UNUSED_PAD src0_sel:WORD_1 src1_sel:DWORD
	v_add3_u32 v103, v185, v103, s24
	v_add3_u32 v105, v184, v105, s24
	v_add3_u32 v99, v176, v99, s24
	v_add3_u32 v97, v177, v97, s24
	v_and_b32_e32 v103, 0xffff0000, v103
	v_and_b32_e32 v105, 0xffff0000, v105
	v_or_b32_sdwa v177, v103, v97 dst_sel:DWORD dst_unused:UNUSED_PAD src0_sel:DWORD src1_sel:WORD_1
	v_or_b32_sdwa v176, v105, v99 dst_sel:DWORD dst_unused:UNUSED_PAD src0_sel:DWORD src1_sel:WORD_1
	v_mov_b32_e32 v184, v37
	v_mov_b32_e32 v185, v39
	global_store_dwordx2 v[174:175], v[176:177], off
	v_mov_b32_e32 v176, v36
	v_mov_b32_e32 v177, v38
	v_pk_mul_f32 v[184:185], v[184:185], v[186:187] op_sel_hi:[1,0]
	v_pk_mul_f32 v[176:177], v[176:177], v[186:187] op_sel_hi:[1,0]
	v_pk_fma_f32 v[184:185], v[136:137], v[184:185], v[2:3]
	v_pk_fma_f32 v[176:177], v[134:135], v[176:177], v[8:9]
	v_and_b32_sdwa v103, v185, v178 dst_sel:DWORD dst_unused:UNUSED_PAD src0_sel:WORD_1 src1_sel:DWORD
	v_and_b32_sdwa v105, v184, v178 dst_sel:DWORD dst_unused:UNUSED_PAD src0_sel:WORD_1 src1_sel:DWORD
	v_and_b32_sdwa v97, v177, v178 dst_sel:DWORD dst_unused:UNUSED_PAD src0_sel:WORD_1 src1_sel:DWORD
	v_and_b32_sdwa v99, v176, v178 dst_sel:DWORD dst_unused:UNUSED_PAD src0_sel:WORD_1 src1_sel:DWORD
	v_add3_u32 v103, v185, v103, s24
	v_add3_u32 v105, v184, v105, s24
	v_add3_u32 v99, v176, v99, s24
	v_add3_u32 v97, v177, v97, s24
	v_and_b32_e32 v103, 0xffff0000, v103
	v_and_b32_e32 v105, 0xffff0000, v105
	v_or_b32_sdwa v177, v103, v97 dst_sel:DWORD dst_unused:UNUSED_PAD src0_sel:DWORD src1_sel:WORD_1
	v_or_b32_sdwa v176, v105, v99 dst_sel:DWORD dst_unused:UNUSED_PAD src0_sel:DWORD src1_sel:WORD_1
	v_mov_b32_e32 v184, v41
	v_mov_b32_e32 v185, v43
	global_store_dwordx2 v[174:175], v[176:177], off offset:512
	v_mov_b32_e32 v176, v40
	v_mov_b32_e32 v177, v42
	v_pk_mul_f32 v[184:185], v[184:185], v[186:187] op_sel_hi:[1,0]
	v_pk_mul_f32 v[176:177], v[176:177], v[186:187] op_sel_hi:[1,0]
	v_pk_fma_f32 v[184:185], v[132:133], v[184:185], v[10:11]
	v_pk_fma_f32 v[176:177], v[130:131], v[176:177], v[20:21]
	v_and_b32_sdwa v103, v185, v178 dst_sel:DWORD dst_unused:UNUSED_PAD src0_sel:WORD_1 src1_sel:DWORD
	v_and_b32_sdwa v105, v184, v178 dst_sel:DWORD dst_unused:UNUSED_PAD src0_sel:WORD_1 src1_sel:DWORD
	v_and_b32_sdwa v97, v177, v178 dst_sel:DWORD dst_unused:UNUSED_PAD src0_sel:WORD_1 src1_sel:DWORD
	v_and_b32_sdwa v99, v176, v178 dst_sel:DWORD dst_unused:UNUSED_PAD src0_sel:WORD_1 src1_sel:DWORD
	v_add3_u32 v103, v185, v103, s24
	v_add3_u32 v105, v184, v105, s24
	v_add3_u32 v99, v176, v99, s24
	v_add3_u32 v97, v177, v97, s24
	v_and_b32_e32 v103, 0xffff0000, v103
	v_and_b32_e32 v105, 0xffff0000, v105
	v_or_b32_sdwa v177, v103, v97 dst_sel:DWORD dst_unused:UNUSED_PAD src0_sel:DWORD src1_sel:WORD_1
	v_or_b32_sdwa v176, v105, v99 dst_sel:DWORD dst_unused:UNUSED_PAD src0_sel:DWORD src1_sel:WORD_1
	v_mov_b32_e32 v184, v45
	v_mov_b32_e32 v185, v47
	global_store_dwordx2 v[174:175], v[176:177], off offset:1024
	v_mov_b32_e32 v176, v44
	v_mov_b32_e32 v177, v46
	v_pk_mul_f32 v[184:185], v[184:185], v[186:187] op_sel_hi:[1,0]
	v_pk_mul_f32 v[176:177], v[176:177], v[186:187] op_sel_hi:[1,0]
	v_pk_fma_f32 v[184:185], v[126:127], v[184:185], v[22:23]
	v_pk_fma_f32 v[176:177], v[124:125], v[176:177], v[24:25]
	v_and_b32_sdwa v103, v185, v178 dst_sel:DWORD dst_unused:UNUSED_PAD src0_sel:WORD_1 src1_sel:DWORD
	v_and_b32_sdwa v105, v184, v178 dst_sel:DWORD dst_unused:UNUSED_PAD src0_sel:WORD_1 src1_sel:DWORD
	v_and_b32_sdwa v97, v177, v178 dst_sel:DWORD dst_unused:UNUSED_PAD src0_sel:WORD_1 src1_sel:DWORD
	v_and_b32_sdwa v99, v176, v178 dst_sel:DWORD dst_unused:UNUSED_PAD src0_sel:WORD_1 src1_sel:DWORD
	v_add3_u32 v103, v185, v103, s24
	v_add3_u32 v105, v184, v105, s24
	v_add3_u32 v99, v176, v99, s24
	v_add3_u32 v97, v177, v97, s24
	v_and_b32_e32 v103, 0xffff0000, v103
	v_and_b32_e32 v105, 0xffff0000, v105
	v_or_b32_sdwa v177, v103, v97 dst_sel:DWORD dst_unused:UNUSED_PAD src0_sel:DWORD src1_sel:WORD_1
	v_or_b32_sdwa v176, v105, v99 dst_sel:DWORD dst_unused:UNUSED_PAD src0_sel:DWORD src1_sel:WORD_1
	v_cmp_gt_i32_e32 vcc, s85, v168
	global_store_dwordx2 v[174:175], v[176:177], off offset:1536
	s_and_saveexec_b64 s[14:15], vcc
	s_cbranch_execz .LBB0_64
	s_and_b64 vcc, exec, s[8:9]
	v_ashrrev_i32_e32 v169, 31, v168
	s_cbranch_vccnz .LBB0_63
	v_lshlrev_b32_e32 v176, 16, v116
	v_and_b32_e32 v177, 0xffff0000, v116
	v_pk_fma_f32 v[48:49], v[4:5], v[176:177], v[48:49]
	v_lshlrev_b32_e32 v176, 16, v117
	v_and_b32_e32 v177, 0xffff0000, v117
	v_pk_fma_f32 v[50:51], v[6:7], v[176:177], v[50:51]
	v_lshlrev_b32_e32 v176, 16, v118
	v_and_b32_e32 v177, 0xffff0000, v118
	v_pk_fma_f32 v[52:53], v[16:17], v[176:177], v[52:53]
	v_lshlrev_b32_e32 v176, 16, v119
	v_and_b32_e32 v177, 0xffff0000, v119
	v_pk_fma_f32 v[54:55], v[18:19], v[176:177], v[54:55]
	v_lshlrev_b32_e32 v176, 16, v120
	v_and_b32_e32 v177, 0xffff0000, v120
	v_pk_fma_f32 v[56:57], v[12:13], v[176:177], v[56:57]
	v_lshlrev_b32_e32 v176, 16, v121
	v_and_b32_e32 v177, 0xffff0000, v121
	v_pk_fma_f32 v[58:59], v[14:15], v[176:177], v[58:59]
	v_lshlrev_b32_e32 v176, 16, v122
	v_and_b32_e32 v177, 0xffff0000, v122
	v_lshlrev_b64 v[174:175], 12, v[168:169]
	v_pk_fma_f32 v[60:61], v[28:29], v[176:177], v[60:61]
	v_lshlrev_b32_e32 v176, 16, v123
	v_and_b32_e32 v177, 0xffff0000, v123
	v_lshl_add_u64 v[174:175], v[148:149], 0, v[174:175]
	v_pk_fma_f32 v[62:63], v[30:31], v[176:177], v[62:63]
	global_store_dwordx4 v[174:175], v[48:51], off nt
	global_store_dwordx4 v[174:175], v[52:55], off offset:1024 nt
	global_store_dwordx4 v[174:175], v[56:59], off offset:2048 nt
	global_store_dwordx4 v[174:175], v[60:63], off offset:3072 nt

.LBB0_64:
	s_or_b64 exec, exec, s[14:15]
	s_mov_b64 s[16:17], -1
	s_and_saveexec_b64 s[14:15], s[4:5]
	s_cbranch_execz .LBB0_51
	v_add_u32_e32 v172, s57, v172
	v_cmp_gt_i32_e32 vcc, s85, v172
	s_and_saveexec_b64 s[4:5], vcc
	s_cbranch_execz .LBB0_68
	v_ashrrev_i32_e32 v173, 31, v172
	v_lshlrev_b64 v[32:33], 12, v[172:173]
	v_lshl_add_u64 v[44:45], v[26:27], 0, v[32:33]
	global_load_dwordx4 v[32:35], v[44:45], off nt
	global_load_dwordx4 v[36:39], v[44:45], off offset:1024 nt
	global_load_dwordx4 v[40:43], v[44:45], off offset:2048 nt
	s_nop 0
	global_load_dwordx4 v[44:47], v[44:45], off offset:3072 nt
	s_and_b64 vcc, exec, s[8:9]
	s_cbranch_vccnz .LBB0_68
	v_lshlrev_b64 v[108:109], 11, v[172:173]
	v_lshl_add_u64 v[114:115], v[146:147], 0, v[108:109]
	global_load_dwordx2 v[108:109], v[114:115], off nt
	global_load_dwordx2 v[110:111], v[114:115], off offset:512 nt
	global_load_dwordx2 v[112:113], v[114:115], off offset:1024 nt
	s_nop 0
	global_load_dwordx2 v[114:115], v[114:115], off offset:1536 nt
.LBB0_68:
	s_or_b64 exec, exec, s[4:5]
	v_add_u32_e32 v174, s57, v168
	v_cmp_gt_i32_e32 vcc, s85, v174
	s_and_saveexec_b64 s[4:5], vcc
	s_cbranch_execz .LBB0_71
	v_ashrrev_i32_e32 v175, 31, v174
	v_lshlrev_b64 v[48:49], 12, v[174:175]
	v_lshl_add_u64 v[60:61], v[26:27], 0, v[48:49]
	global_load_dwordx4 v[48:51], v[60:61], off nt
	global_load_dwordx4 v[52:55], v[60:61], off offset:1024 nt
	global_load_dwordx4 v[56:59], v[60:61], off offset:2048 nt
	s_nop 0
	global_load_dwordx4 v[60:63], v[60:61], off offset:3072 nt
	s_and_b64 vcc, exec, s[8:9]
	s_cbranch_vccnz .LBB0_71
	v_lshlrev_b64 v[116:117], 11, v[174:175]
	v_lshl_add_u64 v[122:123], v[146:147], 0, v[116:117]
	global_load_dwordx2 v[116:117], v[122:123], off nt
	global_load_dwordx2 v[118:119], v[122:123], off offset:512 nt
	global_load_dwordx2 v[120:121], v[122:123], off offset:1024 nt
	s_nop 0
	global_load_dwordx2 v[122:123], v[122:123], off offset:1536 nt
.LBB0_71:
	s_or_b64 exec, exec, s[4:5]
	s_and_b64 vcc, exec, s[8:9]
	s_cbranch_vccnz .LBB0_73
	s_waitcnt vmcnt(7)
	v_lshlrev_b32_e32 v176, 16, v166
	v_and_b32_e32 v177, 0xffff0000, v166
	v_pk_fma_f32 v[92:93], v[4:5], v[176:177], v[92:93]
	v_lshlrev_b32_e32 v176, 16, v167
	v_and_b32_e32 v177, 0xffff0000, v167
	v_pk_fma_f32 v[94:95], v[6:7], v[176:177], v[94:95]
	s_waitcnt vmcnt(6)
	v_lshlrev_b32_e32 v176, 16, v164
	v_and_b32_e32 v177, 0xffff0000, v164
	v_pk_fma_f32 v[88:89], v[16:17], v[176:177], v[88:89]
	v_lshlrev_b32_e32 v176, 16, v165
	v_and_b32_e32 v177, 0xffff0000, v165
	v_pk_fma_f32 v[90:91], v[18:19], v[176:177], v[90:91]
	s_waitcnt vmcnt(5)
	v_lshlrev_b32_e32 v176, 16, v162
	v_and_b32_e32 v177, 0xffff0000, v162
	v_pk_fma_f32 v[84:85], v[12:13], v[176:177], v[84:85]
	v_lshlrev_b32_e32 v176, 16, v163
	v_and_b32_e32 v177, 0xffff0000, v163
	v_pk_fma_f32 v[86:87], v[14:15], v[176:177], v[86:87]
	s_waitcnt vmcnt(4)
	v_lshlrev_b32_e32 v176, 16, v160
	v_and_b32_e32 v177, 0xffff0000, v160
	v_lshlrev_b64 v[172:173], 12, v[170:171]
	v_pk_fma_f32 v[80:81], v[28:29], v[176:177], v[80:81]
	v_lshlrev_b32_e32 v176, 16, v161
	v_and_b32_e32 v177, 0xffff0000, v161
	v_lshl_add_u64 v[172:173], v[148:149], 0, v[172:173]
	v_pk_fma_f32 v[82:83], v[30:31], v[176:177], v[82:83]
	global_store_dwordx4 v[172:173], v[92:95], off nt
	global_store_dwordx4 v[172:173], v[88:91], off offset:1024 nt
	global_store_dwordx4 v[172:173], v[84:87], off offset:2048 nt
	global_store_dwordx4 v[172:173], v[80:83], off offset:3072 nt
.LBB0_73:
	s_waitcnt vmcnt(7)
	v_mul_f32_e32 v107, v93, v93
	s_waitcnt vmcnt(6)
	v_mul_f32_e32 v169, v89, v89
	v_mov_b32_e32 v99, v90
	v_mov_b32_e32 v97, v94
	v_fmac_f32_e32 v107, v92, v92
	v_fmac_f32_e32 v169, v88, v88
	v_fmac_f32_e32 v107, v97, v97
	v_fmac_f32_e32 v169, v99, v99
	v_fmac_f32_e32 v107, v95, v95
	v_fmac_f32_e32 v169, v91, v91
	v_add_f32_e32 v107, v169, v107
	s_waitcnt vmcnt(5)
	v_mul_f32_e32 v169, v85, v85
	v_mov_b32_e32 v103, v86
	v_fmac_f32_e32 v169, v84, v84
	v_fmac_f32_e32 v169, v103, v103
	v_fmac_f32_e32 v169, v87, v87
	v_add_f32_e32 v107, v169, v107
	s_waitcnt vmcnt(4)
	v_mul_f32_e32 v169, v81, v81
	v_mov_b32_e32 v105, v82
	v_fmac_f32_e32 v169, v80, v80
	v_fmac_f32_e32 v169, v105, v105
	v_fmac_f32_e32 v169, v83, v83
	v_add_f32_e32 v107, v169, v107
	ds_swizzle_b32 v169, v107 offset:swizzle(SWAP,1)
	v_mov_b32_e32 v185, v94
	v_mov_b32_e32 v94, v93
	v_mov_b32_e32 v184, v92
	v_lshlrev_b64 v[176:177], 11, v[170:171]
	s_waitcnt lgkmcnt(0)
	v_add_f32_e32 v107, v107, v169
	ds_swizzle_b32 v169, v107 offset:swizzle(SWAP,2)
	v_lshl_add_u64 v[176:177], v[150:151], 0, v[176:177]
	v_add_u32_e32 v168, s53, v168
	s_waitcnt lgkmcnt(0)
	v_add_f32_e32 v107, v107, v169
	ds_swizzle_b32 v169, v107 offset:swizzle(SWAP,4)
	s_waitcnt lgkmcnt(0)
	v_add_f32_e32 v107, v107, v169
	ds_swizzle_b32 v169, v107 offset:swizzle(SWAP,8)
	s_waitcnt lgkmcnt(0)
	v_add_f32_e32 v107, v107, v169
	ds_swizzle_b32 v169, v107 offset:swizzle(SWAP,16)
	s_waitcnt lgkmcnt(0)
	v_add_f32_e32 v107, v107, v169
	v_mov_b32_e32 v169, v107
	s_nop 1
	v_permlane32_swap_b32_e32 v107, v169
	v_add_f32_e32 v107, v107, v169
	v_fmamk_f32 v107, v107, 0x3a800000, v142
	v_cmp_gt_f32_e32 vcc, s35, v107
	v_mul_f32_e32 v169, 0x4b800000, v107
	s_nop 0
	v_cndmask_b32_e32 v107, v107, v169, vcc
	v_rsq_f32_e32 v107, v107
	s_nop 0
	v_mul_f32_e32 v169, 0x45800000, v107
	v_cndmask_b32_e32 v172, v107, v169, vcc
	v_pk_mul_f32 v[186:187], v[94:95], v[172:173] op_sel_hi:[1,0]
	v_pk_mul_f32 v[184:185], v[184:185], v[172:173] op_sel_hi:[1,0]
	v_pk_fma_f32 v[186:187], v[140:141], v[186:187], v[144:145]
	v_pk_fma_f32 v[184:185], v[138:139], v[184:185], v[0:1]
	v_and_b32_sdwa v169, v187, v178 dst_sel:DWORD dst_unused:UNUSED_PAD src0_sel:WORD_1 src1_sel:DWORD
	v_and_b32_sdwa v171, v186, v178 dst_sel:DWORD dst_unused:UNUSED_PAD src0_sel:WORD_1 src1_sel:DWORD
	v_and_b32_sdwa v94, v185, v178 dst_sel:DWORD dst_unused:UNUSED_PAD src0_sel:WORD_1 src1_sel:DWORD
	v_and_b32_sdwa v107, v184, v178 dst_sel:DWORD dst_unused:UNUSED_PAD src0_sel:WORD_1 src1_sel:DWORD
	v_add3_u32 v169, v187, v169, s24
	v_add3_u32 v171, v186, v171, s24
	v_add3_u32 v107, v184, v107, s24
	v_add3_u32 v94, v185, v94, s24
	v_and_b32_e32 v169, 0xffff0000, v169
	v_and_b32_e32 v171, 0xffff0000, v171
	v_or_b32_sdwa v185, v169, v94 dst_sel:DWORD dst_unused:UNUSED_PAD src0_sel:DWORD src1_sel:WORD_1
	v_or_b32_sdwa v184, v171, v107 dst_sel:DWORD dst_unused:UNUSED_PAD src0_sel:DWORD src1_sel:WORD_1
	global_store_dwordx2 v[176:177], v[184:185], off
	v_mov_b32_e32 v185, v90
	v_mov_b32_e32 v90, v89
	v_mov_b32_e32 v184, v88
	v_pk_mul_f32 v[186:187], v[90:91], v[172:173] op_sel_hi:[1,0]
	v_pk_mul_f32 v[184:185], v[184:185], v[172:173] op_sel_hi:[1,0]
	v_pk_fma_f32 v[186:187], v[136:137], v[186:187], v[2:3]
	v_pk_fma_f32 v[184:185], v[134:135], v[184:185], v[8:9]
	v_and_b32_sdwa v107, v187, v178 dst_sel:DWORD dst_unused:UNUSED_PAD src0_sel:WORD_1 src1_sel:DWORD
	v_and_b32_sdwa v169, v186, v178 dst_sel:DWORD dst_unused:UNUSED_PAD src0_sel:WORD_1 src1_sel:DWORD
	v_and_b32_sdwa v90, v185, v178 dst_sel:DWORD dst_unused:UNUSED_PAD src0_sel:WORD_1 src1_sel:DWORD
	v_and_b32_sdwa v94, v184, v178 dst_sel:DWORD dst_unused:UNUSED_PAD src0_sel:WORD_1 src1_sel:DWORD
	v_add3_u32 v107, v187, v107, s24
	v_add3_u32 v169, v186, v169, s24
	v_add3_u32 v94, v184, v94, s24
	v_add3_u32 v90, v185, v90, s24
	v_and_b32_e32 v107, 0xffff0000, v107
	v_and_b32_e32 v169, 0xffff0000, v169
	v_or_b32_sdwa v185, v107, v90 dst_sel:DWORD dst_unused:UNUSED_PAD src0_sel:DWORD src1_sel:WORD_1
	v_or_b32_sdwa v184, v169, v94 dst_sel:DWORD dst_unused:UNUSED_PAD src0_sel:DWORD src1_sel:WORD_1
	global_store_dwordx2 v[176:177], v[184:185], off offset:512
	v_mov_b32_e32 v185, v86
	v_mov_b32_e32 v86, v85
	v_mov_b32_e32 v184, v84
	v_pk_mul_f32 v[186:187], v[86:87], v[172:173] op_sel_hi:[1,0]
	v_pk_mul_f32 v[184:185], v[184:185], v[172:173] op_sel_hi:[1,0]
	v_pk_fma_f32 v[186:187], v[132:133], v[186:187], v[10:11]
	v_pk_fma_f32 v[184:185], v[130:131], v[184:185], v[20:21]
	v_and_b32_sdwa v94, v187, v178 dst_sel:DWORD dst_unused:UNUSED_PAD src0_sel:WORD_1 src1_sel:DWORD
	v_and_b32_sdwa v107, v186, v178 dst_sel:DWORD dst_unused:UNUSED_PAD src0_sel:WORD_1 src1_sel:DWORD
	v_and_b32_sdwa v86, v185, v178 dst_sel:DWORD dst_unused:UNUSED_PAD src0_sel:WORD_1 src1_sel:DWORD
	v_and_b32_sdwa v90, v184, v178 dst_sel:DWORD dst_unused:UNUSED_PAD src0_sel:WORD_1 src1_sel:DWORD
	v_add3_u32 v94, v187, v94, s24
	v_add3_u32 v107, v186, v107, s24
	v_add3_u32 v90, v184, v90, s24
	v_add3_u32 v86, v185, v86, s24
	v_and_b32_e32 v94, 0xffff0000, v94
	v_and_b32_e32 v107, 0xffff0000, v107
	v_or_b32_sdwa v185, v94, v86 dst_sel:DWORD dst_unused:UNUSED_PAD src0_sel:DWORD src1_sel:WORD_1
	v_or_b32_sdwa v184, v107, v90 dst_sel:DWORD dst_unused:UNUSED_PAD src0_sel:DWORD src1_sel:WORD_1
	global_store_dwordx2 v[176:177], v[184:185], off offset:1024
	v_mov_b32_e32 v184, v80
	v_mov_b32_e32 v185, v82
	v_mov_b32_e32 v82, v81
	v_pk_mul_f32 v[184:185], v[184:185], v[172:173] op_sel_hi:[1,0]
	v_pk_mul_f32 v[172:173], v[82:83], v[172:173] op_sel_hi:[1,0]
	v_pk_fma_f32 v[184:185], v[124:125], v[184:185], v[24:25]
	v_pk_fma_f32 v[172:173], v[126:127], v[172:173], v[22:23]
	v_and_b32_sdwa v82, v185, v178 dst_sel:DWORD dst_unused:UNUSED_PAD src0_sel:WORD_1 src1_sel:DWORD
	v_and_b32_sdwa v90, v173, v178 dst_sel:DWORD dst_unused:UNUSED_PAD src0_sel:WORD_1 src1_sel:DWORD
	v_and_b32_sdwa v94, v172, v178 dst_sel:DWORD dst_unused:UNUSED_PAD src0_sel:WORD_1 src1_sel:DWORD
	v_and_b32_sdwa v86, v184, v178 dst_sel:DWORD dst_unused:UNUSED_PAD src0_sel:WORD_1 src1_sel:DWORD
	v_add3_u32 v90, v173, v90, s24
	v_add3_u32 v94, v172, v94, s24
	v_add3_u32 v86, v184, v86, s24
	v_add3_u32 v82, v185, v82, s24
	v_and_b32_e32 v90, 0xffff0000, v90
	v_and_b32_e32 v94, 0xffff0000, v94
	v_or_b32_sdwa v173, v90, v82 dst_sel:DWORD dst_unused:UNUSED_PAD src0_sel:DWORD src1_sel:WORD_1
	v_or_b32_sdwa v172, v94, v86 dst_sel:DWORD dst_unused:UNUSED_PAD src0_sel:DWORD src1_sel:WORD_1
	v_cmp_gt_i32_e32 vcc, s85, v168
	global_store_dwordx2 v[176:177], v[172:173], off offset:1536
	s_and_saveexec_b64 s[4:5], vcc
	s_cbranch_execz .LBB0_50
	s_and_b64 vcc, exec, s[8:9]
	v_ashrrev_i32_e32 v169, 31, v168
	s_cbranch_vccnz .LBB0_49
	v_lshlrev_b32_e32 v176, 16, v158
	v_and_b32_e32 v177, 0xffff0000, v158
	v_pk_fma_f32 v[76:77], v[4:5], v[176:177], v[76:77]
	v_lshlrev_b32_e32 v176, 16, v159
	v_and_b32_e32 v177, 0xffff0000, v159
	v_pk_fma_f32 v[78:79], v[6:7], v[176:177], v[78:79]
	v_lshlrev_b32_e32 v176, 16, v156
	v_and_b32_e32 v177, 0xffff0000, v156
	v_pk_fma_f32 v[72:73], v[16:17], v[176:177], v[72:73]
	v_lshlrev_b32_e32 v176, 16, v157
	v_and_b32_e32 v177, 0xffff0000, v157
	v_pk_fma_f32 v[74:75], v[18:19], v[176:177], v[74:75]
	v_lshlrev_b32_e32 v176, 16, v154
	v_and_b32_e32 v177, 0xffff0000, v154
	v_pk_fma_f32 v[68:69], v[12:13], v[176:177], v[68:69]
	v_lshlrev_b32_e32 v176, 16, v155
	v_and_b32_e32 v177, 0xffff0000, v155
	v_pk_fma_f32 v[70:71], v[14:15], v[176:177], v[70:71]
	v_lshlrev_b32_e32 v176, 16, v152
	v_and_b32_e32 v177, 0xffff0000, v152
	v_lshlrev_b64 v[172:173], 12, v[168:169]
	v_pk_fma_f32 v[64:65], v[28:29], v[176:177], v[64:65]
	v_lshlrev_b32_e32 v176, 16, v153
	v_and_b32_e32 v177, 0xffff0000, v153
	v_lshl_add_u64 v[172:173], v[148:149], 0, v[172:173]
	v_pk_fma_f32 v[66:67], v[30:31], v[176:177], v[66:67]
	global_store_dwordx4 v[172:173], v[76:79], off nt
	global_store_dwordx4 v[172:173], v[72:75], off offset:1024 nt
	global_store_dwordx4 v[172:173], v[68:71], off offset:2048 nt
	global_store_dwordx4 v[172:173], v[64:67], off offset:3072 nt
	s_branch .LBB0_49
.LBB0_76:
	s_or_b64 exec, exec, s[12:13]
	global_load_dwordx4 v[64:67], v[100:101], off nt
.LBB0_77:
	s_or_b64 exec, exec, s[6:7]
	s_add_u32 s4, s0, 0x18000
	s_addc_u32 s5, s1, 0
	s_add_u32 s0, s0, 0x19000
	s_addc_u32 s1, s1, 0
	global_load_dwordx4 v[68:71], v128, s[0:1] nt
	global_load_dwordx4 v[0:3], v128, s[4:5] nt
	s_waitcnt vmcnt(11)
	v_mov_b32_e32 v4, 0
	s_and_b64 vcc, exec, s[8:9]
	s_waitcnt vmcnt(8)
	v_mov_b32_e32 v8, 0
	v_mov_b32_e32 v9, 0
	v_mov_b32_e32 v10, 0
	v_mov_b32_e32 v11, 0
	s_cbranch_vccnz .LBB0_79
	v_readlane_b32 s6, v253, 48
	v_readlane_b32 s7, v253, 49
	s_nop 4
	global_load_dwordx4 v[8:11], v128, s[6:7] nt
.LBB0_79:
	global_load_dwordx4 v[72:75], v[100:101], off offset:1024 nt
	global_load_dwordx4 v[76:79], v102, s[0:1] nt
	global_load_dwordx4 v[12:15], v102, s[4:5] nt
	s_and_b64 vcc, exec, s[8:9]
	v_mov_b32_e32 v5, 0
	v_mov_b32_e32 v6, 0
	v_mov_b32_e32 v7, 0
	s_cbranch_vccnz .LBB0_81
	v_readlane_b32 s6, v253, 48
	v_readlane_b32 s7, v253, 49
	s_nop 4
	global_load_dwordx4 v[4:7], v102, s[6:7] nt
.LBB0_81:
	global_load_dwordx4 v[80:83], v[100:101], off offset:2048 nt
	global_load_dwordx4 v[84:87], v104, s[0:1] nt
	global_load_dwordx4 v[16:19], v104, s[4:5] nt
	s_waitcnt vmcnt(11)
	v_mov_b32_e32 v20, 0
	s_and_b64 vcc, exec, s[8:9]
	s_waitcnt vmcnt(8)
	v_mov_b32_e32 v24, 0
	v_mov_b32_e32 v25, 0
	v_mov_b32_e32 v26, 0
	v_mov_b32_e32 v27, 0
	s_cbranch_vccnz .LBB0_83
	v_readlane_b32 s6, v253, 48
	v_readlane_b32 s7, v253, 49
	s_nop 4
	global_load_dwordx4 v[24:27], v104, s[6:7] nt
.LBB0_83:
	global_load_dwordx4 v[88:91], v[100:101], off offset:3072 nt
	global_load_dwordx4 v[92:95], v106, s[0:1] nt
	global_load_dwordx4 v[28:31], v106, s[4:5] nt
	s_and_b64 vcc, exec, s[8:9]
	v_mov_b32_e32 v21, 0
	v_mov_b32_e32 v22, 0
	v_mov_b32_e32 v23, 0
	s_cbranch_vccnz .LBB0_85
	v_readlane_b32 s0, v253, 48
	v_readlane_b32 s1, v253, 49
	s_nop 4
	global_load_dwordx4 v[20:23], v106, s[0:1] nt
.LBB0_85:
	v_cmp_gt_i32_e64 s[4:5], s18, v98
	s_and_saveexec_b64 s[0:1], s[4:5]
	s_cbranch_execz .LBB0_89
	v_ashrrev_i32_e32 v99, 31, v98
	v_readlane_b32 s68, v253, 1
	v_lshlrev_b64 v[32:33], 12, v[98:99]
	v_readlane_b32 s72, v253, 5
	v_readlane_b32 s73, v253, 6
	s_and_b64 vcc, exec, s[8:9]
	v_readlane_b32 s69, v253, 2
	v_lshl_add_u64 v[32:33], s[72:73], 0, v[32:33]
	v_lshl_add_u64 v[44:45], v[32:33], 0, v[128:129]
	global_load_dwordx4 v[32:35], v[44:45], off nt
	global_load_dwordx4 v[36:39], v[44:45], off offset:1024 nt
	global_load_dwordx4 v[40:43], v[44:45], off offset:2048 nt
	s_nop 0
	global_load_dwordx4 v[44:47], v[44:45], off offset:3072 nt
	v_readlane_b32 s70, v253, 3
	v_readlane_b32 s71, v253, 4
	v_readlane_b32 s74, v253, 7
	v_readlane_b32 s75, v253, 8
	v_readlane_b32 s76, v253, 9
	v_readlane_b32 s77, v253, 10
	v_readlane_b32 s78, v253, 11
	v_readlane_b32 s79, v253, 12
	v_readlane_b32 s80, v253, 13
	v_readlane_b32 s81, v253, 14
	v_readlane_b32 s82, v253, 15
	v_readlane_b32 s83, v253, 16
	s_cbranch_vccnz .LBB0_88
	v_readlane_b32 s6, v253, 46
	v_lshlrev_b64 v[48:49], 11, v[98:99]
	v_readlane_b32 s7, v253, 47
	v_mov_b32_e32 v97, v129
	s_nop 0
	v_lshl_add_u64 v[48:49], s[6:7], 0, v[48:49]
	v_lshl_add_u64 v[48:49], v[48:49], 0, v[96:97]
	global_load_dwordx2 v[100:101], v[48:49], off nt
	global_load_dwordx2 v[102:103], v[48:49], off offset:512 nt
	global_load_dwordx2 v[104:105], v[48:49], off offset:1024 nt
	global_load_dwordx2 v[106:107], v[48:49], off offset:1536 nt

.LBB0_89:
	s_or_b64 exec, exec, s[0:1]
	v_readlane_b32 s0, v253, 41
	s_nop 1
	v_add_u32_e32 v114, s0, v98
	v_cmp_gt_i32_e32 vcc, s18, v114
	s_and_saveexec_b64 s[0:1], vcc
	s_cbranch_execz .LBB0_93
	v_ashrrev_i32_e32 v115, 31, v114
	v_readlane_b32 s68, v253, 1
	v_lshlrev_b64 v[48:49], 12, v[114:115]
	v_readlane_b32 s72, v253, 5
	v_readlane_b32 s73, v253, 6
	s_and_b64 vcc, exec, s[8:9]
	v_readlane_b32 s69, v253, 2
	v_lshl_add_u64 v[48:49], s[72:73], 0, v[48:49]
	v_lshl_add_u64 v[60:61], v[48:49], 0, v[128:129]
	global_load_dwordx4 v[48:51], v[60:61], off nt
	global_load_dwordx4 v[52:55], v[60:61], off offset:1024 nt
	global_load_dwordx4 v[56:59], v[60:61], off offset:2048 nt
	s_nop 0
	global_load_dwordx4 v[60:63], v[60:61], off offset:3072 nt
	v_readlane_b32 s70, v253, 3
	v_readlane_b32 s71, v253, 4
	v_readlane_b32 s74, v253, 7
	v_readlane_b32 s75, v253, 8
	v_readlane_b32 s76, v253, 9
	v_readlane_b32 s77, v253, 10
	v_readlane_b32 s78, v253, 11
	v_readlane_b32 s79, v253, 12
	v_readlane_b32 s80, v253, 13
	v_readlane_b32 s81, v253, 14
	v_readlane_b32 s82, v253, 15
	v_readlane_b32 s83, v253, 16
	s_cbranch_vccnz .LBB0_92
	v_readlane_b32 s6, v253, 46
	v_lshlrev_b64 v[98:99], 11, v[114:115]
	v_readlane_b32 s7, v253, 47
	v_mov_b32_e32 v97, v129
	s_nop 0
	v_lshl_add_u64 v[98:99], s[6:7], 0, v[98:99]
	v_lshl_add_u64 v[112:113], v[98:99], 0, v[96:97]
	global_load_dwordx2 v[98:99], v[112:113], off nt
	global_load_dwordx2 v[108:109], v[112:113], off offset:512 nt
	global_load_dwordx2 v[110:111], v[112:113], off offset:1024 nt
	s_nop 0
	global_load_dwordx2 v[112:113], v[112:113], off offset:1536 nt

.LBB0_98:
	v_readlane_b32 s4, v255, 11
	s_nop 1
	v_add_u32_e32 v158, s4, v182
	v_cmp_gt_i32_e64 s[6:7], s18, v158
	v_ashrrev_i32_e32 v159, 31, v158
	s_and_saveexec_b64 s[4:5], s[6:7]
	s_cbranch_execz .LBB0_101
	v_lshlrev_b64 v[80:81], 12, v[158:159]
	v_lshl_add_u64 v[80:81], v[30:31], 0, v[80:81]
	global_load_dwordx4 v[92:95], v[80:81], off nt
	global_load_dwordx4 v[88:91], v[80:81], off offset:1024 nt
	global_load_dwordx4 v[84:87], v[80:81], off offset:2048 nt
	s_nop 0
	global_load_dwordx4 v[80:83], v[80:81], off offset:3072 nt
	s_and_b64 vcc, exec, s[8:9]
	s_cbranch_vccnz .LBB0_101
	v_lshlrev_b64 v[148:149], 11, v[158:159]
	v_lshl_add_u64 v[148:149], v[134:135], 0, v[148:149]
	global_load_dwordx2 v[154:155], v[148:149], off nt
	global_load_dwordx2 v[152:153], v[148:149], off offset:512 nt
	global_load_dwordx2 v[150:151], v[148:149], off offset:1024 nt
	s_nop 0
	global_load_dwordx2 v[148:149], v[148:149], off offset:1536 nt
.LBB0_101:
	s_or_b64 exec, exec, s[4:5]
	v_readlane_b32 s4, v255, 7
	s_nop 1
	v_add_u32_e32 v156, s4, v182
	v_cmp_gt_i32_e64 s[4:5], s18, v156
	s_and_saveexec_b64 s[14:15], s[4:5]
	s_cbranch_execz .LBB0_104
	v_ashrrev_i32_e32 v157, 31, v156
	v_lshlrev_b64 v[64:65], 12, v[156:157]
	v_lshl_add_u64 v[64:65], v[30:31], 0, v[64:65]
	global_load_dwordx4 v[76:79], v[64:65], off nt
	global_load_dwordx4 v[72:75], v[64:65], off offset:1024 nt
	global_load_dwordx4 v[68:71], v[64:65], off offset:2048 nt
	s_nop 0
	global_load_dwordx4 v[64:67], v[64:65], off offset:3072 nt
	s_and_b64 vcc, exec, s[8:9]
	s_cbranch_vccnz .LBB0_104
	v_lshlrev_b64 v[138:139], 11, v[156:157]
	v_lshl_add_u64 v[138:139], v[134:135], 0, v[138:139]
	global_load_dwordx2 v[146:147], v[138:139], off nt
	global_load_dwordx2 v[144:145], v[138:139], off offset:512 nt
	global_load_dwordx2 v[140:141], v[138:139], off offset:1024 nt
	s_nop 0
	global_load_dwordx2 v[138:139], v[138:139], off offset:1536 nt
.LBB0_104:
	s_or_b64 exec, exec, s[14:15]
	v_add_u32_e32 v160, s52, v182
	s_and_b64 vcc, exec, s[8:9]
	v_ashrrev_i32_e32 v161, 31, v160
	s_cbranch_vccnz .LBB0_106
	v_lshlrev_b32_e32 v164, 16, v100
	v_and_b32_e32 v165, 0xffff0000, v100
	v_pk_fma_f32 v[32:33], v[8:9], v[164:165], v[32:33]
	v_lshlrev_b32_e32 v164, 16, v101
	v_and_b32_e32 v165, 0xffff0000, v101
	v_pk_fma_f32 v[34:35], v[10:11], v[164:165], v[34:35]
	v_lshlrev_b32_e32 v164, 16, v102
	v_and_b32_e32 v165, 0xffff0000, v102
	v_pk_fma_f32 v[36:37], v[4:5], v[164:165], v[36:37]
	v_lshlrev_b32_e32 v164, 16, v103
	v_and_b32_e32 v165, 0xffff0000, v103
	v_pk_fma_f32 v[38:39], v[6:7], v[164:165], v[38:39]
	v_lshlrev_b32_e32 v164, 16, v104
	v_and_b32_e32 v165, 0xffff0000, v104
	v_pk_fma_f32 v[40:41], v[24:25], v[164:165], v[40:41]
	v_lshlrev_b32_e32 v164, 16, v105
	v_and_b32_e32 v165, 0xffff0000, v105
	v_pk_fma_f32 v[42:43], v[26:27], v[164:165], v[42:43]
	v_lshlrev_b32_e32 v164, 16, v106
	v_and_b32_e32 v165, 0xffff0000, v106
	v_lshlrev_b64 v[162:163], 12, v[160:161]
	v_pk_fma_f32 v[44:45], v[20:21], v[164:165], v[44:45]
	v_lshlrev_b32_e32 v164, 16, v107
	v_and_b32_e32 v165, 0xffff0000, v107
	v_lshl_add_u64 v[162:163], v[136:137], 0, v[162:163]
	v_pk_fma_f32 v[46:47], v[22:23], v[164:165], v[46:47]
	global_store_dwordx4 v[162:163], v[32:35], off nt
	global_store_dwordx4 v[162:163], v[36:39], off offset:1024 nt
	global_store_dwordx4 v[162:163], v[40:43], off offset:2048 nt
	global_store_dwordx4 v[162:163], v[44:47], off offset:3072 nt
.LBB0_106:
	v_mul_f32_e32 v128, v33, v33
	v_mul_f32_e32 v157, v37, v37
	v_fmac_f32_e32 v128, v32, v32
	v_fmac_f32_e32 v157, v36, v36
	v_fmac_f32_e32 v128, v34, v34
	v_fmac_f32_e32 v157, v38, v38
	v_fmac_f32_e32 v128, v35, v35
	v_fmac_f32_e32 v157, v39, v39
	v_add_f32_e32 v128, v157, v128
	v_mul_f32_e32 v157, v41, v41
	v_fmac_f32_e32 v157, v40, v40
	v_fmac_f32_e32 v157, v42, v42
	v_fmac_f32_e32 v157, v43, v43
	v_add_f32_e32 v128, v157, v128
	v_mul_f32_e32 v157, v45, v45
	v_fmac_f32_e32 v157, v44, v44
	v_fmac_f32_e32 v157, v46, v46
	v_fmac_f32_e32 v157, v47, v47
	v_add_f32_e32 v128, v157, v128
	ds_swizzle_b32 v157, v128 offset:swizzle(SWAP,1)
	v_mov_b32_e32 v162, v32
	v_mov_b32_e32 v163, v34
	v_mov_b32_e32 v164, v33
	v_mov_b32_e32 v165, v35
	s_waitcnt lgkmcnt(0)
	v_add_f32_e32 v128, v128, v157
	ds_swizzle_b32 v157, v128 offset:swizzle(SWAP,2)
	v_lshlrev_b64 v[160:161], 11, v[160:161]
	v_lshl_add_u64 v[160:161], v[96:97], 0, v[160:161]
	v_readlane_b32 s14, v255, 2
	s_waitcnt lgkmcnt(0)
	v_add_f32_e32 v128, v128, v157
	ds_swizzle_b32 v157, v128 offset:swizzle(SWAP,4)
	s_waitcnt lgkmcnt(0)
	v_add_f32_e32 v128, v128, v157
	ds_swizzle_b32 v157, v128 offset:swizzle(SWAP,8)
	s_waitcnt lgkmcnt(0)
	v_add_f32_e32 v128, v128, v157
	ds_swizzle_b32 v157, v128 offset:swizzle(SWAP,16)
	s_waitcnt lgkmcnt(0)
	v_add_f32_e32 v128, v128, v157
	v_mov_b32_e32 v157, v128
	s_nop 1
	v_permlane32_swap_b32_e32 v128, v157
	v_add_f32_e32 v128, v128, v157
	v_fmamk_f32 v128, v128, 0x3a800000, v142
	v_mul_f32_e32 v157, 0x4b800000, v128
	v_cmp_gt_f32_e32 vcc, s35, v128
	s_nop 1
	v_cndmask_b32_e32 v128, v128, v157, vcc
	v_rsq_f32_e32 v128, v128
	s_nop 0
	v_mul_f32_e32 v157, 0x45800000, v128
	v_cndmask_b32_e32 v128, v128, v157, vcc
	v_pk_mul_f32 v[162:163], v[162:163], v[128:129] op_sel_hi:[1,0]
	v_pk_mul_f32 v[164:165], v[164:165], v[128:129] op_sel_hi:[1,0]
	v_pk_fma_f32 v[162:163], v[126:127], v[162:163], v[0:1]
	v_pk_fma_f32 v[164:165], v[130:131], v[164:165], v[132:133]
	v_and_b32_sdwa v157, v163, v178 dst_sel:DWORD dst_unused:UNUSED_PAD src0_sel:WORD_1 src1_sel:DWORD
	v_and_b32_sdwa v166, v162, v178 dst_sel:DWORD dst_unused:UNUSED_PAD src0_sel:WORD_1 src1_sel:DWORD
	v_add3_u32 v162, v162, v166, s24
	v_add3_u32 v157, v163, v157, s24
	v_and_b32_sdwa v163, v165, v178 dst_sel:DWORD dst_unused:UNUSED_PAD src0_sel:WORD_1 src1_sel:DWORD
	v_and_b32_sdwa v166, v164, v178 dst_sel:DWORD dst_unused:UNUSED_PAD src0_sel:WORD_1 src1_sel:DWORD
	v_add3_u32 v163, v165, v163, s24
	v_add3_u32 v164, v164, v166, s24
	v_and_b32_e32 v163, 0xffff0000, v163
	v_and_b32_e32 v164, 0xffff0000, v164
	v_or_b32_sdwa v163, v163, v157 dst_sel:DWORD dst_unused:UNUSED_PAD src0_sel:DWORD src1_sel:WORD_1
	v_or_b32_sdwa v162, v164, v162 dst_sel:DWORD dst_unused:UNUSED_PAD src0_sel:DWORD src1_sel:WORD_1
	global_store_dwordx2 v[160:161], v[162:163], off
	v_mov_b32_e32 v162, v36
	v_mov_b32_e32 v163, v38
	v_pk_mul_f32 v[162:163], v[162:163], v[128:129] op_sel_hi:[1,0]
	v_mov_b32_e32 v164, v37
	v_mov_b32_e32 v165, v39
	v_pk_fma_f32 v[162:163], v[122:123], v[162:163], v[12:13]
	v_pk_mul_f32 v[164:165], v[164:165], v[128:129] op_sel_hi:[1,0]
	v_and_b32_sdwa v157, v163, v178 dst_sel:DWORD dst_unused:UNUSED_PAD src0_sel:WORD_1 src1_sel:DWORD
	v_pk_fma_f32 v[164:165], v[124:125], v[164:165], v[2:3]
	v_and_b32_sdwa v166, v162, v178 dst_sel:DWORD dst_unused:UNUSED_PAD src0_sel:WORD_1 src1_sel:DWORD
	v_add3_u32 v162, v162, v166, s24
	v_add3_u32 v157, v163, v157, s24
	v_and_b32_sdwa v163, v165, v178 dst_sel:DWORD dst_unused:UNUSED_PAD src0_sel:WORD_1 src1_sel:DWORD
	v_and_b32_sdwa v166, v164, v178 dst_sel:DWORD dst_unused:UNUSED_PAD src0_sel:WORD_1 src1_sel:DWORD
	v_add3_u32 v163, v165, v163, s24
	v_add3_u32 v164, v164, v166, s24
	v_and_b32_e32 v163, 0xffff0000, v163
	v_and_b32_e32 v164, 0xffff0000, v164
	v_or_b32_sdwa v163, v163, v157 dst_sel:DWORD dst_unused:UNUSED_PAD src0_sel:DWORD src1_sel:WORD_1
	v_or_b32_sdwa v162, v164, v162 dst_sel:DWORD dst_unused:UNUSED_PAD src0_sel:DWORD src1_sel:WORD_1
	global_store_dwordx2 v[160:161], v[162:163], off offset:512
	v_mov_b32_e32 v162, v40
	v_mov_b32_e32 v163, v42
	v_pk_mul_f32 v[162:163], v[162:163], v[128:129] op_sel_hi:[1,0]
	v_mov_b32_e32 v164, v41
	v_mov_b32_e32 v165, v43
	v_pk_fma_f32 v[162:163], v[118:119], v[162:163], v[16:17]
	v_pk_mul_f32 v[164:165], v[164:165], v[128:129] op_sel_hi:[1,0]
	v_and_b32_sdwa v157, v163, v178 dst_sel:DWORD dst_unused:UNUSED_PAD src0_sel:WORD_1 src1_sel:DWORD
	v_pk_fma_f32 v[164:165], v[120:121], v[164:165], v[14:15]
	v_and_b32_sdwa v166, v162, v178 dst_sel:DWORD dst_unused:UNUSED_PAD src0_sel:WORD_1 src1_sel:DWORD
	v_add3_u32 v162, v162, v166, s24
	v_add3_u32 v157, v163, v157, s24
	v_and_b32_sdwa v163, v165, v178 dst_sel:DWORD dst_unused:UNUSED_PAD src0_sel:WORD_1 src1_sel:DWORD
	v_and_b32_sdwa v166, v164, v178 dst_sel:DWORD dst_unused:UNUSED_PAD src0_sel:WORD_1 src1_sel:DWORD
	v_add3_u32 v163, v165, v163, s24
	v_add3_u32 v164, v164, v166, s24
	v_and_b32_e32 v163, 0xffff0000, v163
	v_and_b32_e32 v164, 0xffff0000, v164
	v_or_b32_sdwa v163, v163, v157 dst_sel:DWORD dst_unused:UNUSED_PAD src0_sel:DWORD src1_sel:WORD_1
	v_or_b32_sdwa v162, v164, v162 dst_sel:DWORD dst_unused:UNUSED_PAD src0_sel:DWORD src1_sel:WORD_1
	global_store_dwordx2 v[160:161], v[162:163], off offset:1024
	v_mov_b32_e32 v162, v44
	v_mov_b32_e32 v163, v46
	v_pk_mul_f32 v[162:163], v[162:163], v[128:129] op_sel_hi:[1,0]
	v_mov_b32_e32 v164, v45
	v_mov_b32_e32 v165, v47
	v_pk_fma_f32 v[162:163], v[114:115], v[162:163], v[28:29]
	v_pk_mul_f32 v[164:165], v[164:165], v[128:129] op_sel_hi:[1,0]
	v_and_b32_sdwa v128, v163, v178 dst_sel:DWORD dst_unused:UNUSED_PAD src0_sel:WORD_1 src1_sel:DWORD
	v_pk_fma_f32 v[164:165], v[116:117], v[164:165], v[18:19]
	v_and_b32_sdwa v157, v162, v178 dst_sel:DWORD dst_unused:UNUSED_PAD src0_sel:WORD_1 src1_sel:DWORD
	v_add3_u32 v157, v162, v157, s24
	v_add3_u32 v128, v163, v128, s24
	v_and_b32_sdwa v162, v165, v178 dst_sel:DWORD dst_unused:UNUSED_PAD src0_sel:WORD_1 src1_sel:DWORD
	v_and_b32_sdwa v163, v164, v178 dst_sel:DWORD dst_unused:UNUSED_PAD src0_sel:WORD_1 src1_sel:DWORD
	v_add3_u32 v162, v165, v162, s24
	v_add3_u32 v163, v164, v163, s24
	v_and_b32_e32 v162, 0xffff0000, v162
	v_and_b32_e32 v164, 0xffff0000, v163
	v_or_b32_sdwa v163, v162, v128 dst_sel:DWORD dst_unused:UNUSED_PAD src0_sel:DWORD src1_sel:WORD_1
	v_or_b32_sdwa v162, v164, v157 dst_sel:DWORD dst_unused:UNUSED_PAD src0_sel:DWORD src1_sel:WORD_1
	global_store_dwordx2 v[160:161], v[162:163], off offset:1536
	v_add_u32_e32 v160, s14, v182
	v_cmp_gt_i32_e32 vcc, s18, v160
	s_and_saveexec_b64 s[14:15], vcc
	s_cbranch_execz .LBB0_110
	s_and_b64 vcc, exec, s[8:9]
	v_ashrrev_i32_e32 v161, 31, v160
	s_cbranch_vccnz .LBB0_109
	v_lshlrev_b32_e32 v164, 16, v98
	v_and_b32_e32 v165, 0xffff0000, v98
	v_pk_fma_f32 v[48:49], v[8:9], v[164:165], v[48:49]
	v_lshlrev_b32_e32 v164, 16, v99
	v_and_b32_e32 v165, 0xffff0000, v99
	v_pk_fma_f32 v[50:51], v[10:11], v[164:165], v[50:51]
	v_lshlrev_b32_e32 v164, 16, v108
	v_and_b32_e32 v165, 0xffff0000, v108
	v_pk_fma_f32 v[52:53], v[4:5], v[164:165], v[52:53]
	v_lshlrev_b32_e32 v164, 16, v109
	v_and_b32_e32 v165, 0xffff0000, v109
	v_pk_fma_f32 v[54:55], v[6:7], v[164:165], v[54:55]
	v_lshlrev_b32_e32 v164, 16, v110
	v_and_b32_e32 v165, 0xffff0000, v110
	v_pk_fma_f32 v[56:57], v[24:25], v[164:165], v[56:57]
	v_lshlrev_b32_e32 v164, 16, v111
	v_and_b32_e32 v165, 0xffff0000, v111
	v_pk_fma_f32 v[58:59], v[26:27], v[164:165], v[58:59]
	v_lshlrev_b32_e32 v164, 16, v112
	v_and_b32_e32 v165, 0xffff0000, v112
	v_lshlrev_b64 v[162:163], 12, v[160:161]
	v_pk_fma_f32 v[60:61], v[20:21], v[164:165], v[60:61]
	v_lshlrev_b32_e32 v164, 16, v113
	v_and_b32_e32 v165, 0xffff0000, v113
	v_lshl_add_u64 v[162:163], v[136:137], 0, v[162:163]
	v_pk_fma_f32 v[62:63], v[22:23], v[164:165], v[62:63]
	global_store_dwordx4 v[162:163], v[48:51], off nt
	global_store_dwordx4 v[162:163], v[52:55], off offset:1024 nt
	global_store_dwordx4 v[162:163], v[56:59], off offset:2048 nt
	global_store_dwordx4 v[162:163], v[60:63], off offset:3072 nt

.LBB0_110:
	s_or_b64 exec, exec, s[14:15]
	s_mov_b64 s[16:17], -1
	s_and_saveexec_b64 s[14:15], s[6:7]
	s_cbranch_execz .LBB0_97
	v_readlane_b32 s6, v255, 9
	s_nop 1
	v_add_u32_e32 v160, s6, v182
	v_cmp_gt_i32_e32 vcc, s18, v160
	s_and_saveexec_b64 s[6:7], vcc
	s_cbranch_execz .LBB0_114
	v_ashrrev_i32_e32 v161, 31, v160
	v_lshlrev_b64 v[32:33], 12, v[160:161]
	v_lshl_add_u64 v[44:45], v[30:31], 0, v[32:33]
	global_load_dwordx4 v[32:35], v[44:45], off nt
	global_load_dwordx4 v[36:39], v[44:45], off offset:1024 nt
	global_load_dwordx4 v[40:43], v[44:45], off offset:2048 nt
	s_nop 0
	global_load_dwordx4 v[44:47], v[44:45], off offset:3072 nt
	s_and_b64 vcc, exec, s[8:9]
	s_cbranch_vccnz .LBB0_114
	v_lshlrev_b64 v[100:101], 11, v[160:161]
	v_lshl_add_u64 v[106:107], v[134:135], 0, v[100:101]
	global_load_dwordx2 v[100:101], v[106:107], off nt
	global_load_dwordx2 v[102:103], v[106:107], off offset:512 nt
	global_load_dwordx2 v[104:105], v[106:107], off offset:1024 nt
	s_nop 0
	global_load_dwordx2 v[106:107], v[106:107], off offset:1536 nt
.LBB0_114:
	s_or_b64 exec, exec, s[6:7]
	v_readlane_b32 s6, v255, 3
	s_nop 1
	v_add_u32_e32 v160, s6, v182
	v_cmp_gt_i32_e32 vcc, s18, v160
	s_and_saveexec_b64 s[6:7], vcc
	s_cbranch_execz .LBB0_117
	v_ashrrev_i32_e32 v161, 31, v160
	v_lshlrev_b64 v[48:49], 12, v[160:161]
	v_lshl_add_u64 v[60:61], v[30:31], 0, v[48:49]
	global_load_dwordx4 v[48:51], v[60:61], off nt
	global_load_dwordx4 v[52:55], v[60:61], off offset:1024 nt
	global_load_dwordx4 v[56:59], v[60:61], off offset:2048 nt
	s_nop 0
	global_load_dwordx4 v[60:63], v[60:61], off offset:3072 nt
	s_and_b64 vcc, exec, s[8:9]
	s_cbranch_vccnz .LBB0_117
	v_lshlrev_b64 v[98:99], 11, v[160:161]
	v_lshl_add_u64 v[112:113], v[134:135], 0, v[98:99]
	global_load_dwordx2 v[98:99], v[112:113], off nt
	global_load_dwordx2 v[108:109], v[112:113], off offset:512 nt
	global_load_dwordx2 v[110:111], v[112:113], off offset:1024 nt
	s_nop 0
	global_load_dwordx2 v[112:113], v[112:113], off offset:1536 nt
.LBB0_117:
	s_or_b64 exec, exec, s[6:7]
	s_and_b64 vcc, exec, s[8:9]
	s_cbranch_vccnz .LBB0_119
	s_waitcnt vmcnt(7)
	v_lshlrev_b32_e32 v162, 16, v154
	v_and_b32_e32 v163, 0xffff0000, v154
	v_pk_fma_f32 v[92:93], v[8:9], v[162:163], v[92:93]
	v_lshlrev_b32_e32 v162, 16, v155
	v_and_b32_e32 v163, 0xffff0000, v155
	v_pk_fma_f32 v[94:95], v[10:11], v[162:163], v[94:95]
	s_waitcnt vmcnt(6)
	v_lshlrev_b32_e32 v162, 16, v152
	v_and_b32_e32 v163, 0xffff0000, v152
	v_pk_fma_f32 v[88:89], v[4:5], v[162:163], v[88:89]
	v_lshlrev_b32_e32 v162, 16, v153
	v_and_b32_e32 v163, 0xffff0000, v153
	v_pk_fma_f32 v[90:91], v[6:7], v[162:163], v[90:91]
	s_waitcnt vmcnt(5)
	v_lshlrev_b32_e32 v162, 16, v150
	v_and_b32_e32 v163, 0xffff0000, v150
	v_pk_fma_f32 v[84:85], v[24:25], v[162:163], v[84:85]
	v_lshlrev_b32_e32 v162, 16, v151
	v_and_b32_e32 v163, 0xffff0000, v151
	v_pk_fma_f32 v[86:87], v[26:27], v[162:163], v[86:87]
	s_waitcnt vmcnt(4)
	v_lshlrev_b32_e32 v162, 16, v148
	v_and_b32_e32 v163, 0xffff0000, v148
	v_lshlrev_b64 v[160:161], 12, v[158:159]
	v_pk_fma_f32 v[80:81], v[20:21], v[162:163], v[80:81]
	v_lshlrev_b32_e32 v162, 16, v149
	v_and_b32_e32 v163, 0xffff0000, v149
	v_lshl_add_u64 v[160:161], v[136:137], 0, v[160:161]
	v_pk_fma_f32 v[82:83], v[22:23], v[162:163], v[82:83]
	global_store_dwordx4 v[160:161], v[92:95], off nt
	global_store_dwordx4 v[160:161], v[88:91], off offset:1024 nt
	global_store_dwordx4 v[160:161], v[84:87], off offset:2048 nt
	global_store_dwordx4 v[160:161], v[80:83], off offset:3072 nt
.LBB0_119:
	s_waitcnt vmcnt(7)
	v_mul_f32_e32 v157, v93, v93
	s_waitcnt vmcnt(6)
	v_mul_f32_e32 v163, v89, v89
	v_mov_b32_e32 v160, v90
	v_mov_b32_e32 v128, v94
	v_fmac_f32_e32 v157, v92, v92
	v_fmac_f32_e32 v163, v88, v88
	v_fmac_f32_e32 v157, v128, v128
	v_fmac_f32_e32 v163, v160, v160
	v_fmac_f32_e32 v157, v95, v95
	v_fmac_f32_e32 v163, v91, v91
	v_add_f32_e32 v157, v163, v157
	s_waitcnt vmcnt(5)
	v_mul_f32_e32 v163, v85, v85
	v_mov_b32_e32 v161, v86
	v_fmac_f32_e32 v163, v84, v84
	v_fmac_f32_e32 v163, v161, v161
	v_fmac_f32_e32 v163, v87, v87
	v_add_f32_e32 v157, v163, v157
	s_waitcnt vmcnt(4)
	v_mul_f32_e32 v163, v81, v81
	v_mov_b32_e32 v162, v82
	v_fmac_f32_e32 v163, v80, v80
	v_fmac_f32_e32 v163, v162, v162
	v_fmac_f32_e32 v163, v83, v83
	v_add_f32_e32 v157, v163, v157
	ds_swizzle_b32 v163, v157 offset:swizzle(SWAP,1)
	v_mov_b32_e32 v167, v94
	v_mov_b32_e32 v94, v93
	v_mov_b32_e32 v166, v92
	v_lshlrev_b64 v[158:159], 11, v[158:159]
	s_waitcnt lgkmcnt(0)
	v_add_f32_e32 v157, v157, v163
	ds_swizzle_b32 v163, v157 offset:swizzle(SWAP,2)
	v_lshl_add_u64 v[158:159], v[96:97], 0, v[158:159]
	s_waitcnt lgkmcnt(0)
	v_add_f32_e32 v157, v157, v163
	ds_swizzle_b32 v163, v157 offset:swizzle(SWAP,4)
	s_waitcnt lgkmcnt(0)
	v_add_f32_e32 v157, v157, v163
	ds_swizzle_b32 v163, v157 offset:swizzle(SWAP,8)
	s_waitcnt lgkmcnt(0)
	v_add_f32_e32 v157, v157, v163
	ds_swizzle_b32 v163, v157 offset:swizzle(SWAP,16)
	s_waitcnt lgkmcnt(0)
	v_add_f32_e32 v157, v157, v163
	v_mov_b32_e32 v163, v157
	s_nop 1
	v_permlane32_swap_b32_e32 v157, v163
	v_add_f32_e32 v157, v157, v163
	v_fmamk_f32 v157, v157, 0x3a800000, v142
	v_cmp_gt_f32_e32 vcc, s35, v157
	v_mul_f32_e32 v163, 0x4b800000, v157
	s_nop 0
	v_cndmask_b32_e32 v157, v157, v163, vcc
	v_rsq_f32_e32 v157, v157
	s_nop 0
	v_mul_f32_e32 v163, 0x45800000, v157
	v_cndmask_b32_e32 v164, v157, v163, vcc
	v_pk_mul_f32 v[168:169], v[94:95], v[164:165] op_sel_hi:[1,0]
	v_pk_mul_f32 v[166:167], v[166:167], v[164:165] op_sel_hi:[1,0]
	v_pk_fma_f32 v[168:169], v[130:131], v[168:169], v[132:133]
	v_pk_fma_f32 v[166:167], v[126:127], v[166:167], v[0:1]
	v_and_b32_sdwa v163, v169, v178 dst_sel:DWORD dst_unused:UNUSED_PAD src0_sel:WORD_1 src1_sel:DWORD
	v_and_b32_sdwa v165, v168, v178 dst_sel:DWORD dst_unused:UNUSED_PAD src0_sel:WORD_1 src1_sel:DWORD
	v_and_b32_sdwa v94, v167, v178 dst_sel:DWORD dst_unused:UNUSED_PAD src0_sel:WORD_1 src1_sel:DWORD
	v_and_b32_sdwa v157, v166, v178 dst_sel:DWORD dst_unused:UNUSED_PAD src0_sel:WORD_1 src1_sel:DWORD
	v_add3_u32 v163, v169, v163, s24
	v_add3_u32 v165, v168, v165, s24
	v_add3_u32 v157, v166, v157, s24
	v_add3_u32 v94, v167, v94, s24
	v_and_b32_e32 v163, 0xffff0000, v163
	v_and_b32_e32 v165, 0xffff0000, v165
	v_or_b32_sdwa v167, v163, v94 dst_sel:DWORD dst_unused:UNUSED_PAD src0_sel:DWORD src1_sel:WORD_1
	v_or_b32_sdwa v166, v165, v157 dst_sel:DWORD dst_unused:UNUSED_PAD src0_sel:DWORD src1_sel:WORD_1
	global_store_dwordx2 v[158:159], v[166:167], off
	v_mov_b32_e32 v167, v90
	v_mov_b32_e32 v90, v89
	v_mov_b32_e32 v166, v88
	v_pk_mul_f32 v[168:169], v[90:91], v[164:165] op_sel_hi:[1,0]
	v_pk_mul_f32 v[166:167], v[166:167], v[164:165] op_sel_hi:[1,0]
	v_pk_fma_f32 v[168:169], v[124:125], v[168:169], v[2:3]
	v_pk_fma_f32 v[166:167], v[122:123], v[166:167], v[12:13]
	v_and_b32_sdwa v157, v169, v178 dst_sel:DWORD dst_unused:UNUSED_PAD src0_sel:WORD_1 src1_sel:DWORD
	v_and_b32_sdwa v163, v168, v178 dst_sel:DWORD dst_unused:UNUSED_PAD src0_sel:WORD_1 src1_sel:DWORD
	v_and_b32_sdwa v90, v167, v178 dst_sel:DWORD dst_unused:UNUSED_PAD src0_sel:WORD_1 src1_sel:DWORD
	v_and_b32_sdwa v94, v166, v178 dst_sel:DWORD dst_unused:UNUSED_PAD src0_sel:WORD_1 src1_sel:DWORD
	v_add3_u32 v157, v169, v157, s24
	v_add3_u32 v163, v168, v163, s24
	v_add3_u32 v94, v166, v94, s24
	v_add3_u32 v90, v167, v90, s24
	v_and_b32_e32 v157, 0xffff0000, v157
	v_and_b32_e32 v163, 0xffff0000, v163
	v_or_b32_sdwa v167, v157, v90 dst_sel:DWORD dst_unused:UNUSED_PAD src0_sel:DWORD src1_sel:WORD_1
	v_or_b32_sdwa v166, v163, v94 dst_sel:DWORD dst_unused:UNUSED_PAD src0_sel:DWORD src1_sel:WORD_1
	global_store_dwordx2 v[158:159], v[166:167], off offset:512
	v_mov_b32_e32 v167, v86
	v_mov_b32_e32 v86, v85
	v_mov_b32_e32 v166, v84
	v_pk_mul_f32 v[168:169], v[86:87], v[164:165] op_sel_hi:[1,0]
	v_pk_mul_f32 v[166:167], v[166:167], v[164:165] op_sel_hi:[1,0]
	v_pk_fma_f32 v[168:169], v[120:121], v[168:169], v[14:15]
	v_pk_fma_f32 v[166:167], v[118:119], v[166:167], v[16:17]
	v_and_b32_sdwa v94, v169, v178 dst_sel:DWORD dst_unused:UNUSED_PAD src0_sel:WORD_1 src1_sel:DWORD
	v_and_b32_sdwa v157, v168, v178 dst_sel:DWORD dst_unused:UNUSED_PAD src0_sel:WORD_1 src1_sel:DWORD
	v_and_b32_sdwa v86, v167, v178 dst_sel:DWORD dst_unused:UNUSED_PAD src0_sel:WORD_1 src1_sel:DWORD
	v_and_b32_sdwa v90, v166, v178 dst_sel:DWORD dst_unused:UNUSED_PAD src0_sel:WORD_1 src1_sel:DWORD
	v_add3_u32 v94, v169, v94, s24
	v_add3_u32 v157, v168, v157, s24
	v_add3_u32 v90, v166, v90, s24
	v_add3_u32 v86, v167, v86, s24
	v_and_b32_e32 v94, 0xffff0000, v94
	v_and_b32_e32 v157, 0xffff0000, v157
	v_or_b32_sdwa v167, v94, v86 dst_sel:DWORD dst_unused:UNUSED_PAD src0_sel:DWORD src1_sel:WORD_1
	v_or_b32_sdwa v166, v157, v90 dst_sel:DWORD dst_unused:UNUSED_PAD src0_sel:DWORD src1_sel:WORD_1
	global_store_dwordx2 v[158:159], v[166:167], off offset:1024
	v_mov_b32_e32 v166, v80
	v_mov_b32_e32 v167, v82
	v_mov_b32_e32 v82, v81
	v_pk_mul_f32 v[166:167], v[166:167], v[164:165] op_sel_hi:[1,0]
	v_pk_mul_f32 v[164:165], v[82:83], v[164:165] op_sel_hi:[1,0]
	v_pk_fma_f32 v[166:167], v[114:115], v[166:167], v[28:29]
	v_pk_fma_f32 v[164:165], v[116:117], v[164:165], v[18:19]
	v_and_b32_sdwa v82, v167, v178 dst_sel:DWORD dst_unused:UNUSED_PAD src0_sel:WORD_1 src1_sel:DWORD
	v_and_b32_sdwa v90, v165, v178 dst_sel:DWORD dst_unused:UNUSED_PAD src0_sel:WORD_1 src1_sel:DWORD
	v_and_b32_sdwa v94, v164, v178 dst_sel:DWORD dst_unused:UNUSED_PAD src0_sel:WORD_1 src1_sel:DWORD
	v_and_b32_sdwa v86, v166, v178 dst_sel:DWORD dst_unused:UNUSED_PAD src0_sel:WORD_1 src1_sel:DWORD
	v_add3_u32 v90, v165, v90, s24
	v_add3_u32 v94, v164, v94, s24
	v_add3_u32 v86, v166, v86, s24
	v_add3_u32 v82, v167, v82, s24
	v_and_b32_e32 v90, 0xffff0000, v90
	v_and_b32_e32 v94, 0xffff0000, v94
	v_or_b32_sdwa v165, v90, v82 dst_sel:DWORD dst_unused:UNUSED_PAD src0_sel:DWORD src1_sel:WORD_1
	v_or_b32_sdwa v164, v94, v86 dst_sel:DWORD dst_unused:UNUSED_PAD src0_sel:DWORD src1_sel:WORD_1
	global_store_dwordx2 v[158:159], v[164:165], off offset:1536
	s_and_saveexec_b64 s[6:7], s[4:5]
	s_cbranch_execz .LBB0_96
	s_and_b64 vcc, exec, s[8:9]
	v_ashrrev_i32_e32 v157, 31, v156
	s_cbranch_vccnz .LBB0_95
	v_lshlrev_b32_e32 v164, 16, v146
	v_and_b32_e32 v165, 0xffff0000, v146
	v_pk_fma_f32 v[76:77], v[8:9], v[164:165], v[76:77]
	v_lshlrev_b32_e32 v164, 16, v147
	v_and_b32_e32 v165, 0xffff0000, v147
	v_pk_fma_f32 v[78:79], v[10:11], v[164:165], v[78:79]
	v_lshlrev_b32_e32 v164, 16, v144
	v_and_b32_e32 v165, 0xffff0000, v144
	v_pk_fma_f32 v[72:73], v[4:5], v[164:165], v[72:73]
	v_lshlrev_b32_e32 v164, 16, v145
	v_and_b32_e32 v165, 0xffff0000, v145
	v_pk_fma_f32 v[74:75], v[6:7], v[164:165], v[74:75]
	v_lshlrev_b32_e32 v164, 16, v140
	v_and_b32_e32 v165, 0xffff0000, v140
	v_pk_fma_f32 v[68:69], v[24:25], v[164:165], v[68:69]
	v_lshlrev_b32_e32 v164, 16, v141
	v_and_b32_e32 v165, 0xffff0000, v141
	v_pk_fma_f32 v[70:71], v[26:27], v[164:165], v[70:71]
	v_lshlrev_b32_e32 v164, 16, v138
	v_and_b32_e32 v165, 0xffff0000, v138
	v_lshlrev_b64 v[158:159], 12, v[156:157]
	v_pk_fma_f32 v[64:65], v[20:21], v[164:165], v[64:65]
	v_lshlrev_b32_e32 v164, 16, v139
	v_and_b32_e32 v165, 0xffff0000, v139
	v_lshl_add_u64 v[158:159], v[136:137], 0, v[158:159]
	v_pk_fma_f32 v[66:67], v[22:23], v[164:165], v[66:67]
	global_store_dwordx4 v[158:159], v[76:79], off nt
	global_store_dwordx4 v[158:159], v[72:75], off offset:1024 nt
	global_store_dwordx4 v[158:159], v[68:71], off offset:2048 nt
	global_store_dwordx4 v[158:159], v[64:67], off offset:3072 nt
	s_branch .LBB0_95
